# fnet_combine gate load hoisted to loop head; attn_combine wide loads issued with lse loads (one wait)
# speedup vs baseline: 1.0126x; 1.0067x over previous
; __device__ __forceinline__ unsigned cvt_pk_bf16(float lo, float hi) { unsigned r; asm("v_cvt_pk_bf16_f32 %0, %1, %2" : "=v"(r) : "v"(lo), "v"(hi)); return r; }
; __device__ __forceinline__ float bf_lo(unsigned u) { return __uint_as_float(u << 16); }
; __device__ __forceinline__ float bf_hi(unsigned u) { return __uint_as_float(u & 0xffff0000u); }
; __device__ __forceinline__ float sigmoidf_(float x) { return 1.f / (1.f + __expf(-x)); }
; __device__ __forceinline__ void phase_fnet_combine(bf16_t* __restrict__ fg, const float* __restrict__ P, const float* __restrict__ Q, const float* __restrict__ P128, const float* __restrict__ PH, const int S) {
;     ...
;     const float sq = (mid ? 0.f : 1.f) * (klo ? 1.f : -1.f) * (hi ? -1.f : 1.f);
;     bf16_t* gp = fg + t * 4096 + col;
;     const uint4 gt = *(const uint4*)gp;
;     const unsigned gu[4] = {gt.x, gt.y, gt.z, gt.w};
;     float mv[8];
; #pragma unroll
;     for (int e = 0; e < 8; ++e) {
;       float pv, qv;
;       if (!hi) { pv = pw[e]; qv = (l0 + e == 0) ? 0.f : qw[e]; }
;       else if (e == 0) { pv = ps; qv = qs; }
;       else { pv = pw[8 - e]; qv = qw[8 - e]; }
;       mv[e] = (pv - sq * qv) * norm;
;     }
;     unsigned ou[4];
; #pragma unroll
;     for (int q = 0; q < 4; ++q) {
;       const float g0 = bf_lo(gu[q]), g1 = bf_hi(gu[q]);
;       ou[q] = cvt_pk_bf16(mv[2 * q] * g0 * sigmoidf_(g0), mv[2 * q + 1] * g1 * sigmoidf_(g1));
;     }
;     uint4 o; o.x = ou[0]; o.y = ou[1]; o.z = ou[2]; o.w = ou[3];
;     *(uint4*)gp = o;
.LBB0_476:
	s_or_b64 exec, exec, s[46:47]
	v_lshrrev_b64 v[0:1], 9, v[36:37]
	v_and_b32_e32 v2, 0xff8, v44
	v_lshlrev_b64 v[0:1], 13, v[0:1]
	v_cndmask_b32_e64 v3, 1.0, 0, s[4:5]
	v_lshl_add_u64 v[0:1], s[38:39], 0, v[0:1]
	v_lshlrev_b32_e32 v80, 1, v2
	v_cndmask_b32_e64 v3, v3, -v3, s[2:3]
	v_lshl_add_u64 v[20:21], v[0:1], 0, v[80:81]
	v_mul_f32_e32 v10, v3, v49
	s_nop 0
	v_cmp_ne_u32_e64 s[2:3], 0, v45
	s_waitcnt vmcnt(0) lgkmcnt(0)
	v_cndmask_b32_e32 v4, v4, v46, vcc
	v_lshl_add_u64 v[36:37], v[36:37], 0, s[14:15]
	v_cndmask_b32_e64 v6, 0, v16, s[2:3]
	v_cndmask_b32_e32 v6, v6, v47, vcc
	v_fma_f32 v4, -v10, v6, v4
	v_mul_f32_e32 v14, v43, v4
	v_cndmask_b32_e32 v4, v17, v15, vcc
	v_cndmask_b32_e32 v6, v5, v11, vcc
	v_fma_f32 v4, -v4, v10, v6
	v_mul_f32_e32 v16, v43, v4
	v_fma_f32 v4, -v34, v10, v30
	v_mul_f32_e32 v18, v43, v4
	v_cndmask_b32_e32 v4, v19, v13, vcc
	v_cndmask_b32_e32 v6, v7, v9, vcc
	v_fma_f32 v4, -v4, v10, v6
	v_cndmask_b32_e32 v6, v9, v7, vcc
	v_cndmask_b32_e32 v7, v15, v17, vcc
	v_cndmask_b32_e32 v5, v11, v5, vcc
	v_fma_f32 v5, -v7, v10, v5
	v_mul_f32_e32 v23, v43, v4
	v_fma_f32 v4, -v12, v10, v8
	v_mul_f32_e32 v8, v43, v4
	v_cndmask_b32_e32 v4, v13, v19, vcc
	v_fma_f32 v4, -v4, v10, v6
	v_mul_f32_e32 v6, v43, v4
	v_fma_f32 v4, -v26, v10, v22
	v_mul_f32_e32 v4, v43, v4
	v_mul_f32_e32 v5, v43, v5
	v_lshlrev_b32_e32 v7, 16, v100
	v_mul_f32_e32 v9, v14, v7
	v_mul_f32_e32 v7, 0xbfb8aa3b, v7
	v_exp_f32_e32 v7, v7
	v_and_b32_e32 v0, 0xffff0000, v100
	v_add_f32_e32 v7, 1.0, v7
	v_div_scale_f32 v10, s[2:3], v7, v7, 1.0
	v_rcp_f32_e32 v11, v10
	s_nop 0
	v_fma_f32 v12, -v10, v11, 1.0
	v_fmac_f32_e32 v11, v12, v11
	v_div_scale_f32 v12, vcc, 1.0, v7, 1.0
	v_mul_f32_e32 v13, v12, v11
	v_fma_f32 v14, -v10, v13, v12
	v_fmac_f32_e32 v13, v14, v11
	v_fma_f32 v10, -v10, v13, v12
	v_div_fmas_f32 v10, v10, v11, v13
	v_div_fixup_f32 v7, v10, v7, 1.0
	v_mul_f32_e32 v7, v9, v7
	v_mul_f32_e32 v9, v16, v0
	v_mul_f32_e32 v0, 0xbfb8aa3b, v0
	v_exp_f32_e32 v0, v0
	s_nop 0
	v_add_f32_e32 v0, 1.0, v0
	v_div_scale_f32 v10, s[2:3], v0, v0, 1.0
	v_rcp_f32_e32 v11, v10
	s_nop 0
	v_fma_f32 v12, -v10, v11, 1.0
	v_fmac_f32_e32 v11, v12, v11
	v_div_scale_f32 v12, vcc, 1.0, v0, 1.0
	v_mul_f32_e32 v13, v12, v11
	v_fma_f32 v14, -v10, v13, v12
	v_fmac_f32_e32 v13, v14, v11
	v_fma_f32 v10, -v10, v13, v12
	v_div_fmas_f32 v10, v10, v11, v13
	v_div_fixup_f32 v0, v10, v0, 1.0
	v_mul_f32_e32 v0, v9, v0
	v_cvt_pk_bf16_f32 v0, v7, v0
	v_lshlrev_b32_e32 v7, 16, v101
	v_mul_f32_e32 v9, v18, v7
	v_mul_f32_e32 v7, 0xbfb8aa3b, v7
	v_exp_f32_e32 v7, v7
	v_and_b32_e32 v1, 0xffff0000, v101
	v_add_f32_e32 v7, 1.0, v7
	v_div_scale_f32 v10, s[2:3], v7, v7, 1.0
	v_rcp_f32_e32 v11, v10
	s_nop 0
	v_fma_f32 v12, -v10, v11, 1.0
	v_fmac_f32_e32 v11, v12, v11
	v_div_scale_f32 v12, vcc, 1.0, v7, 1.0
	v_mul_f32_e32 v13, v12, v11
	v_fma_f32 v14, -v10, v13, v12
	v_fmac_f32_e32 v13, v14, v11
	v_fma_f32 v10, -v10, v13, v12
	v_div_fmas_f32 v10, v10, v11, v13
	v_div_fixup_f32 v7, v10, v7, 1.0
	v_mul_f32_e32 v7, v9, v7
	v_mul_f32_e32 v9, v23, v1
	v_mul_f32_e32 v1, 0xbfb8aa3b, v1
	v_exp_f32_e32 v1, v1
	s_nop 0
	v_add_f32_e32 v1, 1.0, v1
	v_div_scale_f32 v10, s[2:3], v1, v1, 1.0
	v_rcp_f32_e32 v11, v10
	s_nop 0
	v_fma_f32 v12, -v10, v11, 1.0
	v_fmac_f32_e32 v11, v12, v11
	v_div_scale_f32 v12, vcc, 1.0, v1, 1.0
	v_mul_f32_e32 v13, v12, v11
	v_fma_f32 v14, -v10, v13, v12
	v_fmac_f32_e32 v13, v14, v11
	v_fma_f32 v10, -v10, v13, v12
	v_div_fmas_f32 v10, v10, v11, v13
	v_div_fixup_f32 v1, v10, v1, 1.0
	v_mul_f32_e32 v1, v9, v1
	v_cvt_pk_bf16_f32 v1, v7, v1
	v_lshlrev_b32_e32 v7, 16, v102
	v_mul_f32_e32 v8, v8, v7
	v_mul_f32_e32 v7, 0xbfb8aa3b, v7
	v_exp_f32_e32 v7, v7
	v_and_b32_e32 v2, 0xffff0000, v102
	v_mul_f32_e32 v6, v6, v2
	v_mul_f32_e32 v2, 0xbfb8aa3b, v2
	v_add_f32_e32 v7, 1.0, v7
	v_div_scale_f32 v9, s[2:3], v7, v7, 1.0
	v_rcp_f32_e32 v10, v9
	v_exp_f32_e32 v2, v2
	v_fma_f32 v11, -v9, v10, 1.0
	v_fmac_f32_e32 v10, v11, v10
	v_div_scale_f32 v11, vcc, 1.0, v7, 1.0
	v_mul_f32_e32 v12, v11, v10
	v_fma_f32 v13, -v9, v12, v11
	v_fmac_f32_e32 v12, v13, v10
	v_fma_f32 v9, -v9, v12, v11
	v_div_fmas_f32 v9, v9, v10, v12
	v_div_fixup_f32 v7, v9, v7, 1.0
	v_add_f32_e32 v2, 1.0, v2
	v_mul_f32_e32 v7, v8, v7
	v_div_scale_f32 v8, s[2:3], v2, v2, 1.0
	v_rcp_f32_e32 v9, v8
	s_nop 0
	v_fma_f32 v10, -v8, v9, 1.0
	v_fmac_f32_e32 v9, v10, v9
	v_div_scale_f32 v10, vcc, 1.0, v2, 1.0
	v_mul_f32_e32 v11, v10, v9
	v_fma_f32 v12, -v8, v11, v10
	v_fmac_f32_e32 v11, v12, v9
	v_fma_f32 v8, -v8, v11, v10
	v_div_fmas_f32 v8, v8, v9, v11
	v_div_fixup_f32 v2, v8, v2, 1.0
	v_mul_f32_e32 v2, v6, v2
	v_lshlrev_b32_e32 v6, 16, v103
	v_mul_f32_e32 v4, v4, v6
	v_mul_f32_e32 v6, 0xbfb8aa3b, v6
	v_exp_f32_e32 v6, v6
	v_cvt_pk_bf16_f32 v2, v7, v2
	v_and_b32_e32 v3, 0xffff0000, v103
	v_mul_f32_e32 v5, v5, v3
	v_add_f32_e32 v6, 1.0, v6
	v_div_scale_f32 v7, s[2:3], v6, v6, 1.0
	v_rcp_f32_e32 v8, v7
	v_mul_f32_e32 v3, 0xbfb8aa3b, v3
	v_exp_f32_e32 v3, v3
	v_fma_f32 v9, -v7, v8, 1.0
	v_fmac_f32_e32 v8, v9, v8
	v_div_scale_f32 v9, vcc, 1.0, v6, 1.0
	v_mul_f32_e32 v10, v9, v8
	v_fma_f32 v11, -v7, v10, v9
	v_fmac_f32_e32 v10, v11, v8
	v_fma_f32 v7, -v7, v10, v9
	v_div_fmas_f32 v7, v7, v8, v10
	v_div_fixup_f32 v6, v7, v6, 1.0
	v_add_f32_e32 v3, 1.0, v3
	v_mul_f32_e32 v4, v4, v6
	v_div_scale_f32 v6, s[2:3], v3, v3, 1.0
	v_rcp_f32_e32 v7, v6
	v_readlane_b32 s2, v255, 14
	v_fma_f32 v8, -v6, v7, 1.0
	v_fmac_f32_e32 v7, v8, v7
	v_div_scale_f32 v8, vcc, 1.0, v3, 1.0
	v_mul_f32_e32 v9, v8, v7
	v_fma_f32 v10, -v6, v9, v8
	v_fmac_f32_e32 v9, v10, v7
	v_fma_f32 v6, -v6, v9, v8
	v_div_fmas_f32 v6, v6, v7, v9
	v_add_u32_e32 v44, s2, v44
	s_mov_b64 s[2:3], 0x7fffff
	v_div_fixup_f32 v3, v6, v3, 1.0
	v_cmp_lt_u64_e32 vcc, s[2:3], v[36:37]
	v_mul_f32_e32 v3, v5, v3
	s_or_b64 s[68:69], vcc, s[68:69]
	v_cvt_pk_bf16_f32 v3, v4, v3
	global_store_dwordx4 v[20:21], v[0:3], off
	s_andn2_b64 exec, exec, s[68:69]
	s_cbranch_execz .LBB0_489
; __device__ __forceinline__ int otid() { int t = threadIdx.x; asm volatile("" : "+v"(t)); return t; }
; __device__ __forceinline__ int obid() { extern __shared__ __attribute__((aligned(16))) unsigned char shm_vb[]; return __builtin_amdgcn_readfirstlane(*(volatile LAS int*)((LAS unsigned char*)shm_vb + VB_OFF)); }
; __device__ __forceinline__ void phase_fnet_combine(bf16_t* __restrict__ fg, const float* __restrict__ P, const float* __restrict__ Q, const float* __restrict__ P128, const float* __restrict__ PH, const int S) {
;     ...
;   for (size_t i = (size_t)obid() * 512 + otid(); i < n8; i += gs) {
;     const size_t t = i >> 9; const int col = (int)(i & 511) * 8, g = col >> 8, l0 = col & 255;
;     const int seq = (int)(t / S), k = (int)(t % S);
;     const bool klo = (k <= S / 2); const int kk = klo ? k : S - k;
;     const bool mid = (kk == S / 2), hi = (l0 >= 128);
;     const float* Pr = mid ? PH + seq * 2304 : P + ((size_t)seq * 4096 + kk) * 2048;
;     const float* Qr = Q + ((size_t)seq * 4096 + (mid ? 0 : kk)) * 2048;
;     const int vb = g * 128 + (hi ? 248 - l0 : l0);
;     const f32x4 p0 = *(const f32x4*)(Pr + vb), p1 = *(const f32x4*)(Pr + vb + 4);
;     const f32x4 q0 = *(const f32x4*)(Qr + vb), q1 = *(const f32x4*)(Qr + vb + 4);
;     const float pw[8] = {p0[0], p0[1], p0[2], p0[3], p1[0], p1[1], p1[2], p1[3]}, qw[8] = {q0[0], q0[1], q0[2], q0[3], q1[0], q1[1], q1[2], q1[3]};
;     float ps = 0.f, qs = 0.f;
;     if (hi) {
;       if (l0 == 128) ps = mid ? PH[seq * 2304 + 2048 + g] : P128[((size_t)seq * 4096 + kk) * 16 + g];
;       else { ps = Pr[g * 128 + 256 - l0]; qs = Qr[g * 128 + 256 - l0]; }
;     }
.LBB0_477:
	v_alignbit_b32 v0, v37, v36, 9
	v_lshrrev_b32_e32 v80, s0, v0
	v_and_b32_e32 v0, s1, v0
	v_sub_u32_e32 v1, s17, v0
	v_cmp_lt_u32_e64 s[2:3], s40, v0
	s_nop 1
	v_cndmask_b32_e64 v0, v0, v1, s[2:3]
	v_cmp_eq_u32_e64 s[4:5], s40, v0
	v_cmp_ne_u32_e64 s[6:7], s40, v0
	s_and_saveexec_b64 s[8:9], s[6:7]
	s_xor_b64 s[8:9], exec, s[8:9]
	v_ashrrev_i32_e32 v1, 31, v0
	v_lshlrev_b64 v[2:3], 25, v[80:81]
	v_lshl_add_u64 v[2:3], s[94:95], 0, v[2:3]
	v_lshlrev_b64 v[4:5], 13, v[0:1]
	v_lshl_add_u64 v[2:3], v[2:3], 0, v[4:5]
	v_mov_b64_e32 v[4:5], v[0:1]
	s_andn2_saveexec_b64 s[8:9], s[8:9]
	v_mov_b64_e32 v[2:3], s[44:45]
	s_movk_i32 s13, 0x2400
	v_mad_u64_u32 v[2:3], s[18:19], v80, s13, v[2:3]
	v_mov_b64_e32 v[4:5], 0
	s_or_b64 exec, exec, s[8:9]
	v_lshlrev_b64 v[38:39], 12, v[80:81]
	v_lshl_add_u64 v[4:5], v[4:5], 0, v[38:39]
	v_lshlrev_b64 v[4:5], 13, v[4:5]
	s_movk_i32 s8, 0xf8
	v_and_b32_e32 v45, 0xf8, v44
	v_lshl_add_u64 v[40:41], s[96:97], 0, v[4:5]
	v_bitop3_b32 v4, v44, s8, v44 bitop3:0xc
	s_movk_i32 s8, 0x7f
	v_bfe_u32 v48, v44, 8, 4
	v_cmp_lt_u32_e32 vcc, s8, v45
	v_lshlrev_b32_e32 v1, 7, v48
	v_mov_b32_e32 v13, v81
	v_cndmask_b32_e32 v4, v45, v4, vcc
	v_add_lshl_u32 v12, v1, v4, 2
	v_lshl_add_u64 v[8:9], v[2:3], 0, v[12:13]
	v_lshl_add_u64 v[16:17], v[40:41], 0, v[12:13]
	v_lshl_add_u64 v[104:105], v[36:37], 4, s[38:39]
	global_load_dwordx4 v[100:103], v[104:105], off
	global_load_dwordx4 v[4:7], v[8:9], off
	s_nop 0
	global_load_dwordx4 v[8:11], v[8:9], off offset:16
	s_nop 0
	global_load_dwordx4 v[12:15], v[16:17], off offset:16
	s_nop 0
	global_load_dwordx4 v[16:19], v[16:17], off
	v_mov_b32_e32 v47, 0
	v_mov_b32_e32 v49, 1.0
	v_mov_b32_e32 v46, 0
	s_waitcnt vmcnt(0) lgkmcnt(0)
	v_mov_b64_e32 v[30:31], v[6:7]
	v_mov_b64_e32 v[22:23], v[10:11]
	v_mov_b64_e32 v[26:27], v[14:15]
	v_mov_b64_e32 v[34:35], v[18:19]
	v_mov_b64_e32 v[20:21], v[8:9]
	v_mov_b64_e32 v[28:29], v[4:5]
	v_mov_b64_e32 v[24:25], v[12:13]
	v_mov_b64_e32 v[32:33], v[16:17]
	s_and_saveexec_b64 s[46:47], vcc
	s_cbranch_execz .LBB0_476
	s_movk_i32 s8, 0x80
	v_cmp_ne_u32_e64 s[8:9], s8, v45
	s_and_saveexec_b64 s[18:19], s[8:9]
	s_xor_b64 s[8:9], exec, s[18:19]
	s_cbranch_execz .LBB0_484
	v_sub_u32_e32 v0, v1, v45
	v_add_u32_e32 v80, 0x100, v0
	v_lshlrev_b64 v[0:1], 2, v[80:81]
	v_lshl_add_u64 v[2:3], v[2:3], 0, v[0:1]
	v_lshl_add_u64 v[0:1], v[40:41], 0, v[0:1]
	global_load_dword v46, v[2:3], off
	global_load_dword v47, v[0:1], off

; __device__ __forceinline__ int otid() { int t = threadIdx.x; asm volatile("" : "+v"(t)); return t; }
; __device__ __forceinline__ int obid() { extern __shared__ __attribute__((aligned(16))) unsigned char shm_vb[]; return __builtin_amdgcn_readfirstlane(*(volatile LAS int*)((LAS unsigned char*)shm_vb + VB_OFF)); }
; __device__ __forceinline__ void phase_attn_combine(const bf16_t* __restrict__ qh, const bf16_t* __restrict__ gate, const float* __restrict__ lse, bf16_t* __restrict__ y, const int S) {
;     ...
;   for (size_t i = (size_t)obid() * 512 + otid(); i < n8; i += gs) {
;     const size_t t = i >> 8; const int col = (int)(i & 255) * 8, h16 = col >> 7, dd = col & 127;
;     const int seq = (int)(t / S), n = (int)(t % S);
;     const size_t p0 = t, p1 = (size_t)seq * S + (size_t)(n & 3) * (S >> 2) + (n >> 2), p2 = (size_t)seq * S + (size_t)(n & 15) * (S >> 4) + (n >> 4);
;     const float l0 = lse[(size_t)h16 * TS + p0], l1 = lse[(size_t)(16 + h16) * TS + p1], l2 = lse[(size_t)(32 + h16) * TS + p2];
;     const float mx = fmaxf(l0, fmaxf(l1, l2));
;     float w0 = __expf(l0 - mx), w1 = __expf(l1 - mx), w2 = __expf(l2 - mx);
;     const float wi = 1.f / (w0 + w1 + w2); w0 *= wi; w1 *= wi; w2 *= wi;
;     const uint4 a = *(const uint4*)(qh + ((size_t)h16 * TS + p0) * 128 + dd), b = *(const uint4*)(qh + ((size_t)(16 + h16) * TS + p1) * 128 + dd),
;                 c = *(const uint4*)(qh + ((size_t)(32 + h16) * TS + p2) * 128 + dd);
;     const uint4 gt = *(const uint4*)(gate + t * 2048 + col);
;     const unsigned au[4] = {a.x, a.y, a.z, a.w}, bu[4] = {b.x, b.y, b.z, b.w}, cu[4] = {c.x, c.y, c.z, c.w}, gu[4] = {gt.x, gt.y, gt.z, gt.w};
;     unsigned ou[4];
; #pragma unroll
.LBB0_775:
	v_alignbit_b32 v5, v1, v0, 8
	v_cmp_le_u32_e32 vcc, s17, v5
	v_mov_b32_e32 v6, s17
	v_lshrrev_b64 v[2:3], 8, v[0:1]
	v_cndmask_b32_e32 v6, 0, v6, vcc
	v_sub_u32_e32 v5, v5, v6
	v_and_b32_e32 v80, 3, v5
	v_sub_co_u32_e32 v6, vcc, v2, v5
	v_lshlrev_b64 v[8:9], s0, v[80:81]
	v_lshrrev_b32_e32 v80, 2, v5
	v_and_b32_e32 v10, 15, v5
	v_lshrrev_b32_e32 v12, 4, v5
	v_lshlrev_b32_e32 v5, 10, v0
	v_and_b32_e32 v5, 0x3c000, v5
	v_or_b32_e32 v14, v2, v5
	v_mov_b32_e32 v15, v3
	v_lshl_add_u64 v[16:17], v[14:15], 2, s[36:37]
	v_subbrev_co_u32_e32 v7, vcc, 0, v3, vcc
	global_load_dword v20, v[16:17], off
	v_or_b32_e32 v16, 0x40000, v5
	v_mov_b32_e32 v17, v81
	v_lshl_add_u64 v[16:17], v[6:7], 0, v[16:17]
	v_lshl_add_u64 v[16:17], v[16:17], 0, v[80:81]
	v_or_b32_e32 v80, 0x80000, v5
	v_mov_b32_e32 v11, v81
	v_mov_b32_e32 v13, v81
	v_lshl_add_u64 v[6:7], v[6:7], 0, v[80:81]
	v_lshlrev_b64 v[10:11], s1, v[10:11]
	v_lshl_add_u64 v[6:7], v[6:7], 0, v[12:13]
	v_lshl_add_u64 v[16:17], v[16:17], 0, v[8:9]
	v_lshl_add_u64 v[18:19], v[6:7], 0, v[10:11]
	v_lshl_add_u64 v[8:9], v[16:17], 2, s[36:37]
	v_lshl_add_u64 v[6:7], v[18:19], 2, s[36:37]
	global_load_dword v8, v[8:9], off
	v_lshlrev_b64 v[2:3], 12, v[2:3]
	global_load_dword v5, v[6:7], off
	s_nop 1
	v_lshlrev_b32_e32 v112, 4, v0
	v_and_b32_e32 v114, 0xf0, v112
	v_lshlrev_b64 v[116:117], 8, v[14:15]
	v_lshl_add_u64 v[118:119], s[4:5], 0, v[116:117]
	v_mov_b32_e32 v116, v114
	v_mov_b32_e32 v117, v81
	v_lshl_add_u64 v[120:121], v[118:119], 0, v[116:117]
	global_load_dwordx4 v[96:99], v[120:121], off
	v_lshlrev_b64 v[116:117], 8, v[16:17]
	v_lshl_add_u64 v[118:119], s[4:5], 0, v[116:117]
	v_mov_b32_e32 v116, v114
	v_mov_b32_e32 v117, v81
	v_lshl_add_u64 v[120:121], v[118:119], 0, v[116:117]
	global_load_dwordx4 v[100:103], v[120:121], off
	v_lshlrev_b64 v[116:117], 8, v[18:19]
	v_lshl_add_u64 v[118:119], s[4:5], 0, v[116:117]
	v_mov_b32_e32 v116, v114
	v_mov_b32_e32 v117, v81
	v_lshl_add_u64 v[120:121], v[118:119], 0, v[116:117]
	global_load_dwordx4 v[104:107], v[120:121], off
	v_lshl_add_u64 v[114:115], s[8:9], 0, v[2:3]
	v_and_b32_e32 v116, 0xff0, v112
	v_mov_b32_e32 v118, v116
	v_mov_b32_e32 v119, v81
	v_lshl_add_u64 v[120:121], v[114:115], 0, v[118:119]
	global_load_dwordx4 v[108:111], v[120:121], off
	s_waitcnt lgkmcnt(0)
	s_waitcnt vmcnt(4)
	v_max3_f32 v6, v20, v8, v5
	v_sub_f32_e32 v7, v20, v6
	v_sub_f32_e32 v8, v8, v6
	v_mul_f32_e32 v7, 0x3fb8aa3b, v7
	v_mul_f32_e32 v8, 0x3fb8aa3b, v8
	v_sub_f32_e32 v5, v5, v6
	v_exp_f32_e32 v7, v7
	v_exp_f32_e32 v8, v8
	v_mul_f32_e32 v5, 0x3fb8aa3b, v5
	v_exp_f32_e32 v5, v5
	v_lshlrev_b32_e32 v20, 4, v0
	v_add_f32_e32 v6, v7, v8
	v_and_b32_e32 v80, 0xf0, v20
	v_add_f32_e32 v6, v5, v6
	v_div_scale_f32 v9, s[18:19], v6, v6, 1.0
	v_rcp_f32_e32 v10, v9
	v_lshl_add_u64 v[0:1], v[0:1], 0, s[14:15]
	v_fma_f32 v11, -v9, v10, 1.0
	v_fmac_f32_e32 v10, v11, v10
	v_div_scale_f32 v11, vcc, 1.0, v6, 1.0
	v_mul_f32_e32 v12, v11, v10
	v_fma_f32 v13, -v9, v12, v11
	v_fmac_f32_e32 v12, v13, v10
	v_fma_f32 v9, -v9, v12, v11
	v_div_fmas_f32 v9, v9, v10, v12
	v_div_fixup_f32 v6, v9, v6, 1.0
	v_mul_f32_e32 v22, v7, v6
	v_mul_f32_e32 v23, v8, v6
	v_mul_f32_e32 v5, v5, v6
	v_lshlrev_b64 v[6:7], 8, v[14:15]
	v_lshlrev_b64 v[10:11], 8, v[16:17]
	v_lshl_add_u64 v[6:7], s[4:5], 0, v[6:7]
	v_lshl_add_u64 v[10:11], s[4:5], 0, v[10:11]
	v_lshl_add_u64 v[6:7], v[6:7], 0, v[80:81]
	v_lshl_add_u64 v[10:11], v[10:11], 0, v[80:81]
	v_lshlrev_b64 v[14:15], 8, v[18:19]
	s_nop 0
	v_lshl_add_u64 v[14:15], s[4:5], 0, v[14:15]
	s_nop 0
	v_lshl_add_u64 v[14:15], v[14:15], 0, v[80:81]
	v_lshl_add_u64 v[18:19], s[8:9], 0, v[2:3]
	v_and_b32_e32 v80, 0xff0, v20
	s_nop 0
	v_lshl_add_u64 v[18:19], v[18:19], 0, v[80:81]
	s_nop 0
	v_lshl_add_u64 v[2:3], s[40:41], 0, v[2:3]
	v_lshl_add_u64 v[2:3], v[2:3], 0, v[80:81]
	s_waitcnt lgkmcnt(0)
	s_waitcnt vmcnt(3)
	v_lshlrev_b32_e32 v25, 16, v96
	v_and_b32_e32 v6, 0xffff0000, v96
	s_waitcnt vmcnt(2)
	v_lshlrev_b32_e32 v26, 16, v100
	v_mul_f32_e32 v26, v23, v26
	v_fmac_f32_e32 v26, v22, v25
	v_and_b32_e32 v10, 0xffff0000, v100
	s_waitcnt vmcnt(1)
	v_lshlrev_b32_e32 v25, 16, v104
	v_fmac_f32_e32 v26, v5, v25
	s_waitcnt vmcnt(0)
; __device__ __forceinline__ unsigned cvt_pk_bf16(float lo, float hi) { unsigned r; asm("v_cvt_pk_bf16_f32 %0, %1, %2" : "=v"(r) : "v"(lo), "v"(hi)); return r; }
; __device__ __forceinline__ float bf_lo(unsigned u) { return __uint_as_float(u << 16); }
; __device__ __forceinline__ float bf_hi(unsigned u) { return __uint_as_float(u & 0xffff0000u); }
; __device__ __forceinline__ float sigmoidf_(float x) { return 1.f / (1.f + __expf(-x)); }
; __device__ __forceinline__ void phase_attn_combine(const bf16_t* __restrict__ qh, const bf16_t* __restrict__ gate, const float* __restrict__ lse, bf16_t* __restrict__ y, const int S) {
;     ...
;     for (int k = 0; k < 4; ++k) {
;       const float g0 = bf_lo(gu[k]), g1 = bf_hi(gu[k]);
;       const float y0 = (w0 * bf_lo(au[k]) + w1 * bf_lo(bu[k]) + w2 * bf_lo(cu[k])) * g0 * sigmoidf_(g0);
;       const float y1 = (w0 * bf_hi(au[k]) + w1 * bf_hi(bu[k]) + w2 * bf_hi(cu[k])) * g1 * sigmoidf_(g1);
;       ou[k] = cvt_pk_bf16(y0, y1);
;     }
;     uint4 o; o.x = ou[0]; o.y = ou[1]; o.z = ou[2]; o.w = ou[3];
;     *(uint4*)(y + t * 2048 + col) = o;
	v_lshlrev_b32_e32 v24, 16, v108
	v_mul_f32_e32 v25, v26, v24
	v_mul_f32_e32 v24, 0xbfb8aa3b, v24
	v_exp_f32_e32 v24, v24
	v_mul_f32_e32 v10, v23, v10
	v_fmac_f32_e32 v10, v22, v6
	v_and_b32_e32 v6, 0xffff0000, v104
	v_add_f32_e32 v24, 1.0, v24
	v_div_scale_f32 v26, s[18:19], v24, v24, 1.0
	v_and_b32_e32 v18, 0xffff0000, v108
	v_rcp_f32_e32 v27, v26
	v_fmac_f32_e32 v10, v5, v6
	v_mul_f32_e32 v6, v10, v18
	v_mul_f32_e32 v10, 0xbfb8aa3b, v18
	v_exp_f32_e32 v10, v10
	v_fma_f32 v28, -v26, v27, 1.0
	v_fmac_f32_e32 v27, v28, v27
	v_div_scale_f32 v28, vcc, 1.0, v24, 1.0
	v_mul_f32_e32 v29, v28, v27
	v_add_f32_e32 v10, 1.0, v10
	v_fma_f32 v30, -v26, v29, v28
	v_div_scale_f32 v14, s[18:19], v10, v10, 1.0
	v_fmac_f32_e32 v29, v30, v27
	v_rcp_f32_e32 v18, v14
	v_fma_f32 v26, -v26, v29, v28
	v_div_fmas_f32 v26, v26, v27, v29
	v_div_fixup_f32 v24, v26, v24, 1.0
	v_mul_f32_e32 v24, v25, v24
	v_fma_f32 v25, -v14, v18, 1.0
	v_fmac_f32_e32 v18, v25, v18
	v_div_scale_f32 v25, vcc, 1.0, v10, 1.0
	v_mul_f32_e32 v26, v25, v18
	v_fma_f32 v27, -v14, v26, v25
	v_fmac_f32_e32 v26, v27, v18
	v_fma_f32 v14, -v14, v26, v25
	v_div_fmas_f32 v14, v14, v18, v26
	v_div_fixup_f32 v10, v14, v10, 1.0
	v_mul_f32_e32 v6, v6, v10
	v_lshlrev_b32_e32 v10, 16, v109
	v_and_b32_e32 v14, 0xffff0000, v109
	v_lshlrev_b32_e32 v19, 16, v101
	v_lshlrev_b32_e32 v18, 16, v97
	v_mul_f32_e32 v19, v23, v19
	v_fmac_f32_e32 v19, v22, v18
	v_lshlrev_b32_e32 v18, 16, v105
	v_fmac_f32_e32 v19, v5, v18
	v_mul_f32_e32 v18, v19, v10
	v_mul_f32_e32 v10, 0xbfb8aa3b, v10
	v_exp_f32_e32 v10, v10
	v_and_b32_e32 v11, 0xffff0000, v101
	v_and_b32_e32 v7, 0xffff0000, v97
	v_mul_f32_e32 v11, v23, v11
	v_add_f32_e32 v10, 1.0, v10
	v_div_scale_f32 v19, s[18:19], v10, v10, 1.0
	v_fmac_f32_e32 v11, v22, v7
	v_and_b32_e32 v7, 0xffff0000, v105
	v_cvt_pk_bf16_f32 v6, v24, v6
	v_rcp_f32_e32 v24, v19
	v_fmac_f32_e32 v11, v5, v7
	v_mul_f32_e32 v7, v11, v14
	v_mul_f32_e32 v11, 0xbfb8aa3b, v14
	v_exp_f32_e32 v11, v11
	v_fma_f32 v25, -v19, v24, 1.0
	v_fmac_f32_e32 v24, v25, v24
	v_div_scale_f32 v25, vcc, 1.0, v10, 1.0
	v_mul_f32_e32 v26, v25, v24
	v_add_f32_e32 v11, 1.0, v11
	v_fma_f32 v27, -v19, v26, v25
	v_div_scale_f32 v14, s[18:19], v11, v11, 1.0
	v_fmac_f32_e32 v26, v27, v24
	v_rcp_f32_e32 v15, v14
	v_fma_f32 v19, -v19, v26, v25
	v_div_fmas_f32 v19, v19, v24, v26
	v_div_fixup_f32 v10, v19, v10, 1.0
	v_mul_f32_e32 v10, v18, v10
	v_fma_f32 v18, -v14, v15, 1.0
	v_fmac_f32_e32 v15, v18, v15
	v_div_scale_f32 v18, vcc, 1.0, v11, 1.0
	v_mul_f32_e32 v19, v18, v15
	v_fma_f32 v24, -v14, v19, v18
	v_fmac_f32_e32 v19, v24, v15
	v_fma_f32 v14, -v14, v19, v18
	v_div_fmas_f32 v14, v14, v15, v19
	v_lshlrev_b32_e32 v15, 16, v102
	v_div_fixup_f32 v11, v14, v11, 1.0
	v_lshlrev_b32_e32 v14, 16, v98
	v_mul_f32_e32 v15, v23, v15
	v_mul_f32_e32 v7, v7, v11
	v_fmac_f32_e32 v15, v22, v14
	v_lshlrev_b32_e32 v14, 16, v106
	v_cvt_pk_bf16_f32 v7, v10, v7
	v_lshlrev_b32_e32 v10, 16, v110
	v_fmac_f32_e32 v15, v5, v14
	v_mul_f32_e32 v14, v15, v10
	v_mul_f32_e32 v10, 0xbfb8aa3b, v10
	v_exp_f32_e32 v10, v10
	v_and_b32_e32 v12, 0xffff0000, v102
	v_and_b32_e32 v8, 0xffff0000, v98
	v_mul_f32_e32 v12, v23, v12
	v_add_f32_e32 v10, 1.0, v10
	v_div_scale_f32 v15, s[18:19], v10, v10, 1.0
	v_rcp_f32_e32 v18, v15
	v_fmac_f32_e32 v12, v22, v8
	v_and_b32_e32 v8, 0xffff0000, v106
	v_and_b32_e32 v11, 0xffff0000, v110
	v_fma_f32 v19, -v15, v18, 1.0
	v_fmac_f32_e32 v12, v5, v8
	v_fmac_f32_e32 v18, v19, v18
	v_div_scale_f32 v19, vcc, 1.0, v10, 1.0
	v_mul_f32_e32 v8, v12, v11
	v_mul_f32_e32 v11, 0xbfb8aa3b, v11
	v_mul_f32_e32 v20, v19, v18
	v_exp_f32_e32 v11, v11
	v_fma_f32 v24, -v15, v20, v19
	v_fmac_f32_e32 v20, v24, v18
	v_fma_f32 v15, -v15, v20, v19
	v_div_fmas_f32 v15, v15, v18, v20
	v_add_f32_e32 v11, 1.0, v11
	v_div_fixup_f32 v10, v15, v10, 1.0
	v_div_scale_f32 v12, s[18:19], v11, v11, 1.0
	v_mul_f32_e32 v10, v14, v10
	v_rcp_f32_e32 v14, v12
	s_nop 0
	v_fma_f32 v15, -v12, v14, 1.0
	v_fmac_f32_e32 v14, v15, v14
	v_div_scale_f32 v15, vcc, 1.0, v11, 1.0
	v_mul_f32_e32 v16, v15, v14
	v_fma_f32 v18, -v12, v16, v15
	v_fmac_f32_e32 v16, v18, v14
	v_fma_f32 v12, -v12, v16, v15
	v_div_fmas_f32 v12, v12, v14, v16
	v_lshlrev_b32_e32 v14, 16, v103
	v_div_fixup_f32 v11, v12, v11, 1.0
	v_lshlrev_b32_e32 v12, 16, v99
	v_mul_f32_e32 v14, v23, v14
	v_mul_f32_e32 v8, v8, v11
	v_fmac_f32_e32 v14, v22, v12
	v_lshlrev_b32_e32 v12, 16, v107
	v_cvt_pk_bf16_f32 v8, v10, v8
	v_lshlrev_b32_e32 v10, 16, v111
	v_fmac_f32_e32 v14, v5, v12
	v_mul_f32_e32 v12, v14, v10
	v_mul_f32_e32 v10, 0xbfb8aa3b, v10
	v_exp_f32_e32 v10, v10
	v_and_b32_e32 v9, 0xffff0000, v99
	v_and_b32_e32 v11, 0xffff0000, v111
	v_add_f32_e32 v10, 1.0, v10
	v_div_scale_f32 v14, s[18:19], v10, v10, 1.0
	v_rcp_f32_e32 v15, v14
	s_nop 0
	v_fma_f32 v16, -v14, v15, 1.0
	v_fmac_f32_e32 v15, v16, v15
	v_div_scale_f32 v16, vcc, 1.0, v10, 1.0
	v_mul_f32_e32 v18, v16, v15
	v_fma_f32 v19, -v14, v18, v16
	v_fmac_f32_e32 v18, v19, v15
	v_fma_f32 v14, -v14, v18, v16
	v_div_fmas_f32 v14, v14, v15, v18
	v_div_fixup_f32 v10, v14, v10, 1.0
	v_mul_f32_e32 v10, v12, v10
	v_and_b32_e32 v12, 0xffff0000, v103
	v_mul_f32_e32 v12, v23, v12
	v_fmac_f32_e32 v12, v22, v9
	v_and_b32_e32 v9, 0xffff0000, v107
	v_fmac_f32_e32 v12, v5, v9
	v_mul_f32_e32 v9, 0xbfb8aa3b, v11
	v_exp_f32_e32 v9, v9
	v_mul_f32_e32 v5, v12, v11
	v_add_f32_e32 v9, 1.0, v9
	v_div_scale_f32 v11, s[18:19], v9, v9, 1.0
	v_rcp_f32_e32 v12, v11
	s_mov_b64 s[18:19], 0x3fffff
	v_fma_f32 v13, -v11, v12, 1.0
	v_fmac_f32_e32 v12, v13, v12
	v_div_scale_f32 v13, vcc, 1.0, v9, 1.0
	v_mul_f32_e32 v14, v13, v12
	v_fma_f32 v15, -v11, v14, v13
	v_fmac_f32_e32 v14, v15, v12
	v_fma_f32 v11, -v11, v14, v13
	v_div_fmas_f32 v11, v11, v12, v14
	v_cmp_lt_u64_e32 vcc, s[18:19], v[0:1]
	v_div_fixup_f32 v9, v11, v9, 1.0
	s_or_b64 s[92:93], vcc, s[92:93]
	v_mul_f32_e32 v5, v5, v9
	v_cvt_pk_bf16_f32 v9, v10, v5
	global_store_dwordx4 v[2:3], v[6:9], off
	s_andn2_b64 exec, exec, s[92:93]
	s_cbranch_execnz .LBB0_775
